# attention full tiles: the next tile's LDS stores and the tile-after-next global loads are interleaved into the first 12 QK MFMA gaps instead of running before the MFMA stream
# speedup vs baseline: 1.0089x; 1.0089x over previous
; DI void attn_item(const Params& p, int bh, int qb, unsigned char* smem) {
;     ...
;     for (int jt = 0; jt < ntiles; ++jt) {
;         if (jt + 1 < ntiles) KV_STORE((jt + 1) & 1);
;         if (jt + 2 < ntiles) KV_LOAD(jt + 2);
; #pragma unroll
;         for (int mt = 0; mt < 2; ++mt) {
;         const int key0 = jt * 64 + mt * 32;
;         if (key0 <= wrow0) {
;             const bf16_t* sK = sbase + (jt & 1) * STG + mt * 32 * 200; const bf16_t* sV = sbase + (jt & 1) * STG + KST + mt * 32;
.LBB0_456:
	s_add_i32 s99, s74, 0x82
	s_cmp_ge_u32 s99, s63
	s_cbranch_scc1 .Lattn_slowtop
	s_add_i32 s99, s44, 0xffffffc0
	s_cmp_gt_i32 s99, s62
	s_cbranch_scc1 .Lattn_slowtop
	s_bitcmp1_b32 s74, 0
	s_cselect_b32 s77, 0xac00, 0
	s_cselect_b32 s75, 0, 0xac00
	s_branch .Lattn_fast_il

; #define MFMA(a, b, c) __builtin_amdgcn_mfma_f32_32x32x16_bf16((a), (b), (c), 0, 0, 0)
; DI int crow(int e, int h) { return (e & 3) + 8 * (e >> 2) + 4 * h; }
; DI void attn_item(const Params& p, int bh, int qb, unsigned char* smem) {
;     ...
;         if (jt + 1 < ntiles) KV_STORE((jt + 1) & 1);
;         if (jt + 2 < ntiles) KV_LOAD(jt + 2);
; #pragma unroll
;         for (int mt = 0; mt < 2; ++mt) {
;         const int key0 = jt * 64 + mt * 32;
;         if (key0 <= wrow0) {
;             const bf16_t* sK = sbase + (jt & 1) * STG + mt * 32 * 200; const bf16_t* sV = sbase + (jt & 1) * STG + KST + mt * 32;
;             f32x16 sc; zero_acc(sc);
;             {
;                 bf16x8 kf[12];
; #pragma unroll
;                 for (int ks = 0; ks < 12; ++ks) kf[ks] = *(const bf16x8*)(sK + r * 200 + ks * 16 + h * 8);
; #pragma unroll
;                 for (int ks = 0; ks < 12; ++ks) sc = MFMA(kf[ks], qf[ks], sc);
;                 __builtin_amdgcn_sched_group_barrier(0x100, 6, 0);
; #pragma unroll
;                 for (int q = 0; q < 6; ++q) { __builtin_amdgcn_sched_group_barrier(0x008, 1, 0); __builtin_amdgcn_sched_group_barrier(0x100, 1, 0); }
;                 __builtin_amdgcn_sched_group_barrier(0x008, 6, 0);
;             }
;             if (key0 == wrow0) {
; #pragma unroll
;                 for (int e = 0; e < 16; ++e) if (key0 + crow(e, h) > qrow) sc[e] = -INFINITY;
;             }
;             if (jt == 0 && mt == 0) {
;                 float mx = sc[0];
; #pragma unroll
;                 for (int e = 1; e < 16; ++e) mx = fmaxf(mx, sc[e]);
;                 m_run = fmaxf(mx, __shfl_xor(mx, 32));
;             }
;             float ls = 0.f;
; #pragma unroll
;             for (int e = 0; e < 16; ++e) { const float pv = __builtin_amdgcn_exp2f(sc[e] - m_run); sc[e] = pv; ls += pv; }
;             l_run += ls;
;             bf16x8 pf[2]; pf[0] = pack8<0>(sc); pf[1] = pack8<1>(sc);
;             {
;                 bf16x8 vfr[2][4];
; #pragma unroll
;                 for (int s = 0; s < 2; ++s)
; #pragma unroll
;                     for (int t = 0; t < 4; ++t) vfr[s][t] = ld_frag_perm(sV + (t * 32 + r) * 72 + 16 * s + 4 * h);
; #pragma unroll
;                 for (int s = 0; s < 2; ++s)
; #pragma unroll
;                     for (int t = 0; t < 4; ++t) O[t] = MFMA(vfr[s][t], pf[s], O[t]);
.Lattn_fast_il:
	v_add3_u32 v184, s77, v182, v148
	v_add3_u32 v185, s77, v178, v181
	ds_read_b128 v[204:207], v184 offset:0
	ds_read_b128 v[208:211], v184 offset:32
	ds_read_b128 v[212:215], v184 offset:64
	ds_read_b128 v[216:219], v184 offset:96
	ds_read_b128 v[220:223], v184 offset:128
	ds_read_b128 v[228:231], v184 offset:160
	ds_read_b128 v[232:235], v184 offset:192
	ds_read_b128 v[242:245], v184 offset:224
	v_mov_b32_e32 v224, 0
	v_mov_b32_e32 v225, 0
	v_mov_b32_e32 v226, 0
	v_mov_b32_e32 v183, 0
	s_waitcnt lgkmcnt(7)
	v_mfma_f32_32x32x16_bf16 v[64:79], v[204:207], v[80:83], 0
	ds_read_b128 v[204:207], v184 offset:256
	s_waitcnt vmcnt(0)
	v_add3_u32 v188, s75, v169, v170
	ds_write_b128 v188, v[128:131]
	s_waitcnt lgkmcnt(8)
	v_mfma_f32_32x32x16_bf16 v[64:79], v[208:211], v[84:87], v[64:79]
	ds_read_b128 v[208:211], v184 offset:288
	v_add3_u32 v189, s75, v171, v172
	ds_write_b128 v189, v[132:135]
	s_waitcnt lgkmcnt(9)
	v_mfma_f32_32x32x16_bf16 v[64:79], v[212:215], v[88:91], v[64:79]
	ds_read_b128 v[212:215], v184 offset:320
	v_add3_u32 v190, s75, v173, v174
	ds_write_b128 v190, v[136:139]
	s_waitcnt lgkmcnt(10)
	v_mfma_f32_32x32x16_bf16 v[64:79], v[216:219], v[92:95], v[64:79]
	ds_read_b128 v[216:219], v184 offset:352
	v_lshl_add_u32 v191, v168, 1, s75
	v_add_u32_e32 v192, v191, v175
	v_add_u32_e32 v191, v191, v176
	s_waitcnt lgkmcnt(10)
	v_mfma_f32_32x32x16_bf16 v[64:79], v[220:223], v[96:99], v[64:79]
	ds_read_b128 v[220:223], v184 offset:12800
	v_add_u32_e32 v193, s98, v192
	v_subrev_u32_e32 v194, s98, v192
	v_add_u32_e32 v195, s98, v191
	v_subrev_u32_e32 v196, s98, v191
	s_waitcnt lgkmcnt(10)
	v_mfma_f32_32x32x16_bf16 v[64:79], v[228:231], v[100:103], v[64:79]
	ds_read_b128 v[228:231], v184 offset:12832
	ds_write_b64 v193, v[140:141] offset:25600
	ds_write_b64 v194, v[142:143] offset:25608
	ds_write_b64 v195, v[144:145] offset:25600
	ds_write_b64 v196, v[146:147] offset:25608
	s_waitcnt lgkmcnt(14)
	v_mfma_f32_32x32x16_bf16 v[64:79], v[232:235], v[104:107], v[64:79]
	ds_read_b128 v[232:235], v184 offset:12864
	v_add_u32_e32 v188, s44, v165
	v_mad_i64_i32 v[188:189], s[76:77], v188, s56, v[156:157]
	v_add_u32_e32 v190, s44, v166
	s_waitcnt lgkmcnt(14)
	v_mfma_f32_32x32x16_bf16 v[64:79], v[242:245], v[108:111], v[64:79]
	ds_read_b128 v[242:245], v184 offset:12896
	v_mad_i64_i32 v[190:191], s[76:77], v190, s56, v[158:159]
	global_load_dwordx4 v[128:131], v[188:189], off
	global_load_dwordx4 v[132:135], v[190:191], off
	s_waitcnt lgkmcnt(14)
	v_mfma_f32_32x32x16_bf16 v[64:79], v[204:207], v[112:115], v[64:79]
	ds_read_b128 v[204:207], v184 offset:12928
	v_add_u32_e32 v188, s44, v167
	v_mad_i64_i32 v[188:189], s[76:77], v188, s56, v[160:161]
	v_lshl_add_u64 v[190:191], s[44:45], 1, v[150:151]
	s_waitcnt lgkmcnt(13)
	v_mfma_f32_32x32x16_bf16 v[64:79], v[208:211], v[116:119], v[64:79]
	ds_read_b128 v[208:211], v184 offset:12960
	v_lshl_add_u64 v[192:193], v[190:191], 0, v[152:153]
	global_load_dwordx4 v[136:139], v[188:189], off
	global_load_dwordx4 v[140:143], v[192:193], off
	s_waitcnt lgkmcnt(12)
	v_mfma_f32_32x32x16_bf16 v[64:79], v[212:215], v[120:123], v[64:79]
	ds_read_b128 v[212:215], v184 offset:12992
	v_lshl_add_u64 v[188:189], v[190:191], 0, v[154:155]
	global_load_dwordx4 v[144:147], v[188:189], off
	s_waitcnt lgkmcnt(11)
	v_mfma_f32_32x32x16_bf16 v[64:79], v[216:219], v[124:127], v[64:79]
	ds_read_b128 v[216:219], v184 offset:13024
	s_waitcnt lgkmcnt(11)
	v_mfma_f32_32x32x16_bf16 v[188:203], v[220:223], v[80:83], 0
	ds_read_b128 v[220:223], v184 offset:13056
	s_waitcnt lgkmcnt(11)
	v_mfma_f32_32x32x16_bf16 v[188:203], v[228:231], v[84:87], v[188:203]
	ds_read_b128 v[228:231], v184 offset:13088
	s_waitcnt lgkmcnt(7)
	v_mfma_f32_32x32x16_bf16 v[188:203], v[232:235], v[88:91], v[188:203]
	ds_read_b128 v[232:235], v184 offset:13120
	s_nop 1
	v_sub_f32_e32 v186, v64, v179
	v_exp_f32_e32 v64, v186
	v_sub_f32_e32 v187, v65, v179
	v_exp_f32_e32 v65, v187
	v_sub_f32_e32 v186, v66, v179
	v_exp_f32_e32 v66, v186
	s_waitcnt lgkmcnt(7)
	v_mfma_f32_32x32x16_bf16 v[188:203], v[242:245], v[92:95], v[188:203]
	ds_read_b128 v[242:245], v184 offset:13152
	v_add_f32_e32 v224, v64, v224
	v_sub_f32_e32 v187, v67, v179
	v_exp_f32_e32 v67, v187
	v_add_f32_e32 v225, v65, v225
	v_sub_f32_e32 v186, v68, v179
	v_exp_f32_e32 v68, v186
	s_waitcnt lgkmcnt(7)
	v_mfma_f32_32x32x16_bf16 v[188:203], v[204:207], v[96:99], v[188:203]
	ds_read_b64 v[204:205], v185 offset:25600
	ds_read_b64 v[206:207], v185 offset:25616
	v_add_f32_e32 v224, v66, v224
	v_sub_f32_e32 v187, v69, v179
	v_exp_f32_e32 v69, v187
	v_add_f32_e32 v225, v67, v225
	v_sub_f32_e32 v186, v70, v179
	v_exp_f32_e32 v70, v186
	s_waitcnt lgkmcnt(8)
	v_mfma_f32_32x32x16_bf16 v[188:203], v[208:211], v[100:103], v[188:203]
	ds_read_b64 v[208:209], v185 offset:30208
	ds_read_b64 v[210:211], v185 offset:30224
	v_add_f32_e32 v224, v68, v224
	v_sub_f32_e32 v187, v71, v179
	v_exp_f32_e32 v71, v187
	v_add_f32_e32 v225, v69, v225
	v_add_f32_e32 v224, v70, v224
	v_add_f32_e32 v225, v71, v225
	s_waitcnt lgkmcnt(9)
	v_mfma_f32_32x32x16_bf16 v[188:203], v[212:215], v[104:107], v[188:203]
	ds_read_b64 v[212:213], v185 offset:34816
	ds_read_b64 v[214:215], v185 offset:34832
	v_cvt_pk_bf16_f32 v64, v64, v65
	v_cvt_pk_bf16_f32 v65, v66, v67
	v_cvt_pk_bf16_f32 v66, v68, v69
	v_cvt_pk_bf16_f32 v67, v70, v71
	s_waitcnt lgkmcnt(10)
	v_mfma_f32_32x32x16_bf16 v[188:203], v[216:219], v[108:111], v[188:203]
	ds_read_b64 v[216:217], v185 offset:39424
	ds_read_b64 v[218:219], v185 offset:39440
	v_sub_f32_e32 v186, v72, v179
	v_exp_f32_e32 v72, v186
	v_sub_f32_e32 v187, v73, v179
	v_exp_f32_e32 v73, v187
	v_sub_f32_e32 v186, v74, v179
	v_exp_f32_e32 v74, v186
	s_waitcnt lgkmcnt(11)
; #define MFMA(a, b, c) __builtin_amdgcn_mfma_f32_32x32x16_bf16((a), (b), (c), 0, 0, 0)
; DI void attn_item(const Params& p, int bh, int qb, unsigned char* smem) {
;     ...
;             float ls = 0.f;
; #pragma unroll
;             for (int e = 0; e < 16; ++e) { const float pv = __builtin_amdgcn_exp2f(sc[e] - m_run); sc[e] = pv; ls += pv; }
;             l_run += ls;
;             bf16x8 pf[2]; pf[0] = pack8<0>(sc); pf[1] = pack8<1>(sc);
;             {
;                 bf16x8 vfr[2][4];
; #pragma unroll
;                 for (int s = 0; s < 2; ++s)
; #pragma unroll
;                     for (int t = 0; t < 4; ++t) vfr[s][t] = ld_frag_perm(sV + (t * 32 + r) * 72 + 16 * s + 4 * h);
; #pragma unroll
;                 for (int s = 0; s < 2; ++s)
; #pragma unroll
;                     for (int t = 0; t < 4; ++t) O[t] = MFMA(vfr[s][t], pf[s], O[t]);
;                 __builtin_amdgcn_sched_group_barrier(0x100, 8, 0);
; #pragma unroll
;                 for (int q = 0; q < 4; ++q) { __builtin_amdgcn_sched_group_barrier(0x008, 1, 0); __builtin_amdgcn_sched_group_barrier(0x100, 2, 0); }
;                 __builtin_amdgcn_sched_group_barrier(0x008, 4, 0);
	v_mfma_f32_32x32x16_bf16 v[188:203], v[220:223], v[112:115], v[188:203]
	ds_read_b64 v[220:221], v185 offset:25632
	ds_read_b64 v[222:223], v185 offset:25648
	v_add_f32_e32 v224, v72, v224
	v_sub_f32_e32 v187, v75, v179
	v_exp_f32_e32 v75, v187
	v_add_f32_e32 v225, v73, v225
	v_sub_f32_e32 v186, v76, v179
	v_exp_f32_e32 v76, v186
	s_waitcnt lgkmcnt(12)
	v_mfma_f32_32x32x16_bf16 v[188:203], v[228:231], v[116:119], v[188:203]
	ds_read_b64 v[228:229], v185 offset:30240
	ds_read_b64 v[230:231], v185 offset:30256
	v_add_f32_e32 v224, v74, v224
	v_sub_f32_e32 v187, v77, v179
	v_exp_f32_e32 v77, v187
	v_add_f32_e32 v225, v75, v225
	v_sub_f32_e32 v186, v78, v179
	v_exp_f32_e32 v78, v186
	s_waitcnt lgkmcnt(13)
	v_mfma_f32_32x32x16_bf16 v[188:203], v[232:235], v[120:123], v[188:203]
	ds_read_b64 v[232:233], v185 offset:34848
	ds_read_b64 v[234:235], v185 offset:34864
	v_add_f32_e32 v224, v76, v224
	v_sub_f32_e32 v187, v79, v179
	v_exp_f32_e32 v79, v187
	v_add_f32_e32 v225, v77, v225
	v_add_f32_e32 v224, v78, v224
	v_add_f32_e32 v225, v79, v225
	s_waitcnt lgkmcnt(14)
	v_mfma_f32_32x32x16_bf16 v[188:203], v[242:245], v[124:127], v[188:203]
	ds_read_b64 v[242:243], v185 offset:39456
	ds_read_b64 v[244:245], v185 offset:39472
	v_cvt_pk_bf16_f32 v68, v72, v73
	v_cvt_pk_bf16_f32 v69, v74, v75
	v_cvt_pk_bf16_f32 v70, v76, v77
	v_cvt_pk_bf16_f32 v71, v78, v79
	v_add_f32_e32 v224, v224, v225
	v_add_f32_e32 v180, v180, v224
	s_waitcnt lgkmcnt(14)
	v_mfma_f32_32x32x16_bf16 v[48:63], v[204:207], v[64:67], v[48:63]
	ds_read_b64 v[204:205], v185 offset:25664
	ds_read_b64 v[206:207], v185 offset:25680
	s_waitcnt lgkmcnt(14)
	v_mfma_f32_32x32x16_bf16 v[32:47], v[208:211], v[64:67], v[32:47]
	ds_read_b64 v[208:209], v185 offset:30272
	ds_read_b64 v[210:211], v185 offset:30288
	v_sub_f32_e32 v186, v188, v179
	v_exp_f32_e32 v188, v186
	v_sub_f32_e32 v187, v189, v179
	v_exp_f32_e32 v189, v187
	v_sub_f32_e32 v186, v190, v179
	v_exp_f32_e32 v190, v186
	s_waitcnt lgkmcnt(14)
	v_mfma_f32_32x32x16_bf16 v[16:31], v[212:215], v[64:67], v[16:31]
	ds_read_b64 v[212:213], v185 offset:34880
	ds_read_b64 v[214:215], v185 offset:34896
	v_add_f32_e32 v226, v188, v226
	v_sub_f32_e32 v187, v191, v179
	v_exp_f32_e32 v191, v187
	v_add_f32_e32 v183, v189, v183
	v_sub_f32_e32 v186, v192, v179
	v_exp_f32_e32 v192, v186
	s_waitcnt lgkmcnt(14)
	v_mfma_f32_32x32x16_bf16 v[0:15], v[216:219], v[64:67], v[0:15]
	ds_read_b64 v[216:217], v185 offset:39488
	ds_read_b64 v[218:219], v185 offset:39504
	v_add_f32_e32 v226, v190, v226
	v_sub_f32_e32 v187, v193, v179
	v_exp_f32_e32 v193, v187
	v_add_f32_e32 v183, v191, v183
	v_sub_f32_e32 v186, v194, v179
	v_exp_f32_e32 v194, v186
	s_waitcnt lgkmcnt(14)
	v_mfma_f32_32x32x16_bf16 v[48:63], v[220:223], v[68:71], v[48:63]
	ds_read_b64 v[220:221], v185 offset:25696
	ds_read_b64 v[222:223], v185 offset:25712
	v_add_f32_e32 v226, v192, v226
	v_sub_f32_e32 v187, v195, v179
	v_exp_f32_e32 v195, v187
	v_add_f32_e32 v183, v193, v183
	v_add_f32_e32 v226, v194, v226
	v_add_f32_e32 v183, v195, v183
	s_waitcnt lgkmcnt(14)
	v_mfma_f32_32x32x16_bf16 v[32:47], v[228:231], v[68:71], v[32:47]
	ds_read_b64 v[228:229], v185 offset:30304
	ds_read_b64 v[230:231], v185 offset:30320
	v_cvt_pk_bf16_f32 v188, v188, v189
	v_cvt_pk_bf16_f32 v189, v190, v191
	v_cvt_pk_bf16_f32 v190, v192, v193
	v_cvt_pk_bf16_f32 v191, v194, v195
	s_waitcnt lgkmcnt(14)
	v_mfma_f32_32x32x16_bf16 v[16:31], v[232:235], v[68:71], v[16:31]
	ds_read_b64 v[232:233], v185 offset:34912
	ds_read_b64 v[234:235], v185 offset:34928
	v_sub_f32_e32 v186, v196, v179
	v_exp_f32_e32 v196, v186
	v_sub_f32_e32 v187, v197, v179
	v_exp_f32_e32 v197, v187
	v_sub_f32_e32 v186, v198, v179
	v_exp_f32_e32 v198, v186
	s_waitcnt lgkmcnt(14)
	v_mfma_f32_32x32x16_bf16 v[0:15], v[242:245], v[68:71], v[0:15]
	ds_read_b64 v[242:243], v185 offset:39520
	ds_read_b64 v[244:245], v185 offset:39536
	v_add_f32_e32 v226, v196, v226
	v_sub_f32_e32 v187, v199, v179
	v_exp_f32_e32 v199, v187
	v_add_f32_e32 v183, v197, v183
	v_sub_f32_e32 v186, v200, v179
	v_exp_f32_e32 v200, v186
	s_waitcnt lgkmcnt(14)
	v_mfma_f32_32x32x16_bf16 v[48:63], v[204:207], v[188:191], v[48:63]
	v_add_f32_e32 v226, v198, v226
	v_sub_f32_e32 v187, v201, v179
	v_exp_f32_e32 v201, v187
	v_add_f32_e32 v183, v199, v183
	v_sub_f32_e32 v186, v202, v179
	v_exp_f32_e32 v202, v186
	s_waitcnt lgkmcnt(12)
	v_mfma_f32_32x32x16_bf16 v[32:47], v[208:211], v[188:191], v[32:47]
	v_add_f32_e32 v226, v200, v226
	v_sub_f32_e32 v187, v203, v179
	v_exp_f32_e32 v203, v187
	v_add_f32_e32 v183, v201, v183
	v_add_f32_e32 v226, v202, v226
	v_add_f32_e32 v183, v203, v183
	s_waitcnt lgkmcnt(10)
	v_mfma_f32_32x32x16_bf16 v[16:31], v[212:215], v[188:191], v[16:31]
	v_cvt_pk_bf16_f32 v192, v196, v197
	v_cvt_pk_bf16_f32 v193, v198, v199
	v_cvt_pk_bf16_f32 v194, v200, v201
	v_cvt_pk_bf16_f32 v195, v202, v203
	v_add_f32_e32 v226, v226, v183
	v_add_f32_e32 v180, v180, v226
	s_waitcnt lgkmcnt(8)
	v_mfma_f32_32x32x16_bf16 v[0:15], v[216:219], v[188:191], v[0:15]
	s_waitcnt lgkmcnt(6)
	v_mfma_f32_32x32x16_bf16 v[48:63], v[220:223], v[192:195], v[48:63]
	s_waitcnt lgkmcnt(4)
	v_mfma_f32_32x32x16_bf16 v[32:47], v[228:231], v[192:195], v[32:47]
	s_waitcnt lgkmcnt(2)
	v_mfma_f32_32x32x16_bf16 v[16:31], v[232:235], v[192:195], v[16:31]
	s_waitcnt lgkmcnt(0)
	v_mfma_f32_32x32x16_bf16 v[0:15], v[242:245], v[192:195], v[0:15]
	s_branch .LBB0_455
